# one-time s_sleep phase offset for the second wave per SIMD before the sel and win loops
# baseline (speedup 1.0000x reference)
.LBB0_807:
	s_waitcnt lgkmcnt(0)
	s_barrier
	ds_read_b64 v[162:163], v187
	s_lshl_b64 s[0:1], s[68:69], 18
	v_sub_u32_e32 v209, v210, v184
	s_waitcnt lgkmcnt(0)
	ds_bpermute_b32 v0, v220, v162
	ds_bpermute_b32 v1, v220, v163
	s_waitcnt lgkmcnt(1)
	v_or_b32_e32 v0, v0, v162
	s_waitcnt lgkmcnt(0)
	v_or_b32_e32 v1, v1, v163
	ds_bpermute_b32 v2, v221, v0
	ds_bpermute_b32 v3, v221, v1
	s_waitcnt lgkmcnt(1)
	v_or_b32_e32 v0, v2, v0
	s_waitcnt lgkmcnt(0)
	v_or_b32_e32 v1, v3, v1
	ds_bpermute_b32 v2, v222, v0
	ds_bpermute_b32 v3, v222, v1
	s_waitcnt lgkmcnt(1)
	v_or_b32_e32 v0, v2, v0
	s_waitcnt lgkmcnt(0)
	v_or_b32_e32 v1, v3, v1
	ds_bpermute_b32 v2, v223, v0
	ds_bpermute_b32 v3, v223, v1
	s_waitcnt lgkmcnt(1)
	v_or_b32_e32 v0, v2, v0
	s_waitcnt lgkmcnt(0)
	v_or_b32_e32 v1, v3, v1
	ds_bpermute_b32 v2, v224, v0
	ds_bpermute_b32 v3, v224, v1
	s_waitcnt lgkmcnt(1)
	v_or_b32_e32 v0, v2, v0
	s_waitcnt lgkmcnt(0)
	v_or_b32_e32 v1, v3, v1
	v_readfirstlane_b32 s8, v0
	v_readfirstlane_b32 s9, v1
	s_cmp_eq_u64 s[8:9], 0
	s_cbranch_scc1 .LBB0_818
	s_cmp_eq_u32 s53, 0
	s_cbranch_scc1 .Lsel_nodelay
	s_sleep 5
.Lsel_nodelay:
	s_ff1_i32_b64 s14, s[8:9]
	s_lshl_b64 s[2:3], s[0:1], 1
	s_lshl_b32 s21, s14, 6
	s_lshl_b32 s15, s14, 12
	s_cmp_lt_i32 s21, s91
	s_cselect_b64 s[12:13], -1, 0
	s_add_u32 s16, s8, -1
	s_addc_u32 s17, s9, -1
	v_cndmask_b32_e64 v2, 0, 1, s[12:13]
	s_and_b64 s[12:13], s[12:13], exec
	v_lshl_add_u64 v[210:211], v[198:199], 0, s[2:3]
	s_cselect_b32 s13, -1, s17
	s_cselect_b32 s12, -1, s16
	s_lshl_b32 s62, s14, 13
	v_lshl_add_u64 v[0:1], v[210:211], 0, s[62:63]
	global_load_dwordx4 v[128:131], v[0:1], off
	global_load_dwordx4 v[132:135], v[0:1], off offset:1024
	global_load_dwordx4 v[136:139], v[0:1], off offset:2048
	global_load_dwordx4 v[140:143], v[0:1], off offset:3072
	v_mov_b32_e32 v214, 0
	v_lshl_add_u64 v[212:213], v[200:201], 0, s[2:3]
	s_and_b64 s[8:9], s[12:13], s[8:9]
	v_readfirstlane_b32 s2, v2
	v_mov_b32_e32 v215, 0
	s_mov_b32 s62, s15
	v_mov_b32_e32 v16, 0
	v_mov_b32_e32 v17, v214
	v_mov_b32_e32 v18, v214
	v_mov_b32_e32 v19, v214
	v_mov_b32_e32 v20, v214
	v_mov_b32_e32 v21, v214
	v_mov_b32_e32 v22, v214
	v_mov_b32_e32 v23, v214
	v_mov_b32_e32 v24, v214
	v_mov_b32_e32 v25, v214
	v_mov_b32_e32 v26, v214
	v_mov_b32_e32 v27, v214
	v_mov_b32_e32 v28, v214
	v_mov_b32_e32 v29, v214
	v_mov_b32_e32 v30, v214
	v_mov_b32_e32 v31, v214
	v_mov_b32_e32 v0, 0
	v_mov_b32_e32 v1, v214
	v_mov_b32_e32 v2, v214
	v_mov_b32_e32 v3, v214
	v_mov_b32_e32 v4, v214
	v_mov_b32_e32 v5, v214
	v_mov_b32_e32 v6, v214
	v_mov_b32_e32 v7, v214
	v_mov_b32_e32 v8, v214
	v_mov_b32_e32 v9, v214
	v_mov_b32_e32 v10, v214
	v_mov_b32_e32 v11, v214
	v_mov_b32_e32 v12, v214
	v_mov_b32_e32 v13, v214
	v_mov_b32_e32 v14, v214
	v_mov_b32_e32 v15, v214
	v_mov_b32_e32 v48, 0
	v_mov_b32_e32 v49, v214
	v_mov_b32_e32 v50, v214
	v_mov_b32_e32 v51, v214
	v_mov_b32_e32 v52, v214
	v_mov_b32_e32 v53, v214
	v_mov_b32_e32 v54, v214
	v_mov_b32_e32 v55, v214
	v_mov_b32_e32 v56, v214
	v_mov_b32_e32 v57, v214
	v_mov_b32_e32 v58, v214
	v_mov_b32_e32 v59, v214
	v_mov_b32_e32 v60, v214
	v_mov_b32_e32 v61, v214
	v_mov_b32_e32 v62, v214
	v_mov_b32_e32 v63, v214
	v_mov_b32_e32 v32, 0
	v_mov_b32_e32 v33, v214
	v_mov_b32_e32 v34, v214
	v_mov_b32_e32 v35, v214
	v_mov_b32_e32 v36, v214
	v_mov_b32_e32 v37, v214
	v_mov_b32_e32 v38, v214
	v_mov_b32_e32 v39, v214
	v_mov_b32_e32 v40, v214
	v_mov_b32_e32 v41, v214
	v_mov_b32_e32 v42, v214
	v_mov_b32_e32 v43, v214
	v_mov_b32_e32 v44, v214
	v_mov_b32_e32 v45, v214
	v_mov_b32_e32 v46, v214
	v_mov_b32_e32 v47, v214

.LBB0_819:
	v_and_b32_e32 v64, 0xffff0000, v164
	v_mul_f32_e32 v64, 0xbfb8aa3b, v64
	v_exp_f32_e32 v64, v64
	v_lshlrev_b32_e32 v65, 16, v166
	v_mul_f32_e32 v65, 0xbfb8aa3b, v65
	v_exp_f32_e32 v65, v65
	v_add_f32_e32 v64, 1.0, v64
	v_div_scale_f32 v66, s[2:3], v64, v64, 1.0
	v_rcp_f32_e32 v67, v66
	v_div_scale_f32 v70, vcc, 1.0, v64, 1.0
	v_add_f32_e32 v65, 1.0, v65
	v_fma_f32 v68, -v66, v67, 1.0
	v_fmac_f32_e32 v67, v68, v67
	v_mul_f32_e32 v71, v70, v67
	v_fma_f32 v68, -v66, v71, v70
	v_fmac_f32_e32 v71, v68, v67
	global_load_dwordx2 v[68:69], v[160:161], off
	v_fma_f32 v66, -v66, v71, v70
	v_div_scale_f32 v70, s[2:3], v65, v65, 1.0
	v_rcp_f32_e32 v72, v70
	v_div_fmas_f32 v66, v66, v67, v71
	ds_bpermute_b32 v67, v177, v215
	v_div_fixup_f32 v64, v66, v64, 1.0
	v_fma_f32 v66, -v70, v72, 1.0
	v_fmac_f32_e32 v72, v66, v72
	v_div_scale_f32 v66, vcc, 1.0, v65, 1.0
	v_mul_f32_e32 v71, v66, v72
	v_fma_f32 v73, -v70, v71, v66
	v_fmac_f32_e32 v71, v73, v72
	s_waitcnt lgkmcnt(0)
	v_add_f32_e32 v73, v215, v67
	v_div_scale_f32 v74, s[2:3], v73, v73, 1.0
	v_rcp_f32_e32 v75, v74
	v_fma_f32 v70, -v70, v71, v66
	v_div_fmas_f32 v70, v70, v72, v71
	v_div_fixup_f32 v65, v70, v65, 1.0
	v_fma_f32 v70, -v74, v75, 1.0
	v_fmac_f32_e32 v75, v70, v75
	v_div_scale_f32 v70, vcc, 1.0, v73, 1.0
	v_mul_f32_e32 v71, v70, v75
	v_fma_f32 v72, -v74, v71, v70
	v_fmac_f32_e32 v71, v72, v75
	ds_bpermute_b32 v72, v177, v214
	v_fma_f32 v70, -v74, v71, v70
	v_div_fmas_f32 v70, v70, v75, v71
	v_div_fixup_f32 v70, v70, v73, 1.0
	v_cmp_lt_f32_e32 vcc, 0, v73
	s_waitcnt lgkmcnt(0)
	v_add_f32_e32 v74, v214, v72
	v_div_scale_f32 v75, s[2:3], v74, v74, 1.0
	v_rcp_f32_e32 v76, v75
	v_cndmask_b32_e32 v72, 0, v70, vcc
	v_mul_f32_e32 v72, v64, v72
	global_load_dwordx2 v[66:67], v[160:161], off offset:64
	v_fma_f32 v64, -v75, v76, 1.0
	v_fmac_f32_e32 v76, v64, v76
	v_div_scale_f32 v64, vcc, 1.0, v74, 1.0
	v_mul_f32_e32 v73, v64, v76
	v_fma_f32 v77, -v75, v73, v64
	v_fmac_f32_e32 v73, v77, v76
	v_fma_f32 v64, -v75, v73, v64
	v_div_fmas_f32 v64, v64, v76, v73
	v_div_fixup_f32 v64, v64, v74, 1.0
	v_cmp_lt_f32_e32 vcc, 0, v74
	global_load_dwordx2 v[74:75], v[160:161], off offset:80
	global_load_dwordx2 v[70:71], v[160:161], off offset:16
	v_pk_mul_f32 v[62:63], v[62:63], v[72:73] op_sel_hi:[1,0]
	v_pk_mul_f32 v[60:61], v[60:61], v[72:73] op_sel_hi:[1,0]
	v_pk_mul_f32 v[58:59], v[58:59], v[72:73] op_sel_hi:[1,0]
	v_pk_mul_f32 v[56:57], v[56:57], v[72:73] op_sel_hi:[1,0]
	v_pk_mul_f32 v[54:55], v[54:55], v[72:73] op_sel_hi:[1,0]
	v_pk_mul_f32 v[52:53], v[52:53], v[72:73] op_sel_hi:[1,0]
	v_pk_mul_f32 v[50:51], v[50:51], v[72:73] op_sel_hi:[1,0]
	v_pk_mul_f32 v[76:77], v[48:49], v[72:73] op_sel_hi:[1,0]
	v_pk_mul_f32 v[48:49], v[44:45], v[72:73] op_sel_hi:[1,0]
	v_pk_mul_f32 v[44:45], v[46:47], v[72:73] op_sel_hi:[1,0]
	v_pk_mul_f32 v[46:47], v[40:41], v[72:73] op_sel_hi:[1,0]
	v_pk_mul_f32 v[40:41], v[42:43], v[72:73] op_sel_hi:[1,0]
	v_pk_mul_f32 v[36:37], v[36:37], v[72:73] op_sel_hi:[1,0]
	v_pk_mul_f32 v[38:39], v[38:39], v[72:73] op_sel_hi:[1,0]
	v_pk_mul_f32 v[32:33], v[32:33], v[72:73] op_sel_hi:[1,0]
	v_pk_mul_f32 v[34:35], v[34:35], v[72:73] op_sel_hi:[1,0]
	global_load_dwordx2 v[42:43], v[160:161], off offset:32
	global_load_dwordx2 v[72:73], v[160:161], off offset:48
	v_pk_mov_b32 v[80:81], v[76:77], v[50:51] op_sel:[1,0]
	v_mov_b32_e32 v77, v51
	v_cndmask_b32_e32 v64, 0, v64, vcc
	v_mul_f32_e32 v64, v65, v64
	s_max_i32 s2, s91, 0x200
	s_add_i32 s21, s2, 0xfffffe00
	v_mov_b32_e32 v163, 0
	s_lshr_b32 s3, s21, 5
	s_ashr_i32 s2, s91, 5
	s_waitcnt vmcnt(5)
	v_and_b32_e32 v78, 0xffff0000, v68
	v_lshlrev_b32_e32 v79, 16, v69
	v_lshlrev_b32_e32 v68, 16, v68
	v_and_b32_e32 v69, 0xffff0000, v69
	v_pk_add_f32 v[78:79], v[80:81], v[78:79]
	v_pk_add_f32 v[50:51], v[76:77], v[68:69]
	v_and_b32_sdwa v68, v78, v232 dst_sel:DWORD dst_unused:UNUSED_PAD src0_sel:WORD_1 src1_sel:DWORD
	v_add3_u32 v68, v78, v68, s81
	v_and_b32_sdwa v76, v50, v232 dst_sel:DWORD dst_unused:UNUSED_PAD src0_sel:WORD_1 src1_sel:DWORD
	v_and_b32_e32 v68, 0xffff0000, v68
	v_and_b32_sdwa v69, v51, v232 dst_sel:DWORD dst_unused:UNUSED_PAD src0_sel:WORD_1 src1_sel:DWORD
	v_add3_u32 v50, v50, v76, s81
	v_add3_u32 v51, v51, v69, s81
	v_or_b32_sdwa v50, v50, v68 dst_sel:DWORD dst_unused:UNUSED_PAD src0_sel:WORD_1 src1_sel:DWORD
	global_load_dwordx2 v[68:69], v[160:161], off offset:96
	global_load_dwordx2 v[76:77], v[160:161], off offset:112
	v_and_b32_sdwa v65, v79, v232 dst_sel:DWORD dst_unused:UNUSED_PAD src0_sel:WORD_1 src1_sel:DWORD
	v_add3_u32 v65, v79, v65, s81
	v_mov_b32_e32 v81, v34
	v_mov_b32_e32 v34, v33
	v_and_b32_e32 v51, 0xffff0000, v51
	v_mov_b32_e32 v80, v32
	v_or_b32_sdwa v51, v51, v65 dst_sel:DWORD dst_unused:UNUSED_PAD src0_sel:DWORD src1_sel:WORD_1
	s_cmp_gt_i32 s3, s2
	v_mov_b32_e32 v162, v163
	s_waitcnt vmcnt(6)
	v_lshlrev_b32_e32 v79, 16, v67
	v_lshlrev_b32_e32 v78, 16, v66
	v_and_b32_e32 v67, 0xffff0000, v67
	v_and_b32_e32 v66, 0xffff0000, v66
	v_pk_add_f32 v[32:33], v[34:35], v[66:67]
	v_pk_add_f32 v[78:79], v[80:81], v[78:79]
	v_and_b32_sdwa v65, v33, v232 dst_sel:DWORD dst_unused:UNUSED_PAD src0_sel:WORD_1 src1_sel:DWORD
	v_and_b32_sdwa v66, v32, v232 dst_sel:DWORD dst_unused:UNUSED_PAD src0_sel:WORD_1 src1_sel:DWORD
	v_and_b32_sdwa v34, v79, v232 dst_sel:DWORD dst_unused:UNUSED_PAD src0_sel:WORD_1 src1_sel:DWORD
	v_and_b32_sdwa v35, v78, v232 dst_sel:DWORD dst_unused:UNUSED_PAD src0_sel:WORD_1 src1_sel:DWORD
	v_add3_u32 v33, v33, v65, s81
	v_add3_u32 v32, v32, v66, s81
	v_add3_u32 v35, v78, v35, s81
	v_add3_u32 v34, v79, v34, s81
	v_and_b32_e32 v33, 0xffff0000, v33
	v_and_b32_e32 v32, 0xffff0000, v32
	v_or_b32_sdwa v33, v33, v34 dst_sel:DWORD dst_unused:UNUSED_PAD src0_sel:DWORD src1_sel:WORD_1
	v_or_b32_sdwa v32, v32, v35 dst_sel:DWORD dst_unused:UNUSED_PAD src0_sel:DWORD src1_sel:WORD_1
	global_store_dwordx2 v[160:161], v[50:51], off
	global_store_dwordx2 v[160:161], v[32:33], off offset:64
	s_waitcnt vmcnt(6)
	v_and_b32_e32 v32, 0xffff0000, v70
	v_lshlrev_b32_e32 v33, 16, v71
	v_pk_mov_b32 v[50:51], v[52:53], v[54:55] op_sel:[1,0]
	v_lshlrev_b32_e32 v34, 16, v70
	v_and_b32_e32 v35, 0xffff0000, v71
	v_pk_add_f32 v[32:33], v[50:51], v[32:33]
	v_mov_b32_e32 v53, v55
	v_pk_add_f32 v[34:35], v[52:53], v[34:35]
	v_and_b32_sdwa v50, v33, v232 dst_sel:DWORD dst_unused:UNUSED_PAD src0_sel:WORD_1 src1_sel:DWORD
	v_and_b32_sdwa v51, v32, v232 dst_sel:DWORD dst_unused:UNUSED_PAD src0_sel:WORD_1 src1_sel:DWORD
	v_add3_u32 v33, v33, v50, s81
	v_and_b32_sdwa v50, v35, v232 dst_sel:DWORD dst_unused:UNUSED_PAD src0_sel:WORD_1 src1_sel:DWORD
	v_add3_u32 v32, v32, v51, s81
	v_and_b32_sdwa v51, v34, v232 dst_sel:DWORD dst_unused:UNUSED_PAD src0_sel:WORD_1 src1_sel:DWORD
	v_add3_u32 v35, v35, v50, s81
	v_and_b32_e32 v32, 0xffff0000, v32
	v_add3_u32 v34, v34, v51, s81
	v_and_b32_e32 v35, 0xffff0000, v35
	v_or_b32_sdwa v33, v35, v33 dst_sel:DWORD dst_unused:UNUSED_PAD src0_sel:DWORD src1_sel:WORD_1
	v_or_b32_sdwa v32, v34, v32 dst_sel:DWORD dst_unused:UNUSED_PAD src0_sel:WORD_1 src1_sel:DWORD
	v_lshlrev_b32_e32 v35, 16, v75
	v_lshlrev_b32_e32 v34, 16, v74
	v_mov_b32_e32 v52, v36
	v_mov_b32_e32 v53, v38
	v_and_b32_e32 v51, 0xffff0000, v75
	v_and_b32_e32 v50, 0xffff0000, v74
	v_pk_add_f32 v[34:35], v[52:53], v[34:35]
	v_mov_b32_e32 v38, v37
	v_pk_add_f32 v[36:37], v[38:39], v[50:51]
	v_and_b32_sdwa v38, v35, v232 dst_sel:DWORD dst_unused:UNUSED_PAD src0_sel:WORD_1 src1_sel:DWORD
	v_and_b32_sdwa v39, v34, v232 dst_sel:DWORD dst_unused:UNUSED_PAD src0_sel:WORD_1 src1_sel:DWORD
	v_add3_u32 v34, v34, v39, s81
	v_add3_u32 v35, v35, v38, s81
	v_and_b32_sdwa v38, v37, v232 dst_sel:DWORD dst_unused:UNUSED_PAD src0_sel:WORD_1 src1_sel:DWORD
	v_and_b32_sdwa v39, v36, v232 dst_sel:DWORD dst_unused:UNUSED_PAD src0_sel:WORD_1 src1_sel:DWORD
	v_add3_u32 v37, v37, v38, s81
	v_add3_u32 v36, v36, v39, s81
	v_and_b32_e32 v37, 0xffff0000, v37
	v_and_b32_e32 v36, 0xffff0000, v36
	v_or_b32_sdwa v35, v37, v35 dst_sel:DWORD dst_unused:UNUSED_PAD src0_sel:DWORD src1_sel:WORD_1
	v_or_b32_sdwa v34, v36, v34 dst_sel:DWORD dst_unused:UNUSED_PAD src0_sel:DWORD src1_sel:WORD_1
	global_store_dwordx2 v[160:161], v[32:33], off offset:16
	global_store_dwordx2 v[160:161], v[34:35], off offset:80
	s_waitcnt vmcnt(7)
	v_and_b32_e32 v32, 0xffff0000, v42
	v_lshlrev_b32_e32 v33, 16, v43
	v_pk_mov_b32 v[36:37], v[56:57], v[58:59] op_sel:[1,0]
	v_lshlrev_b32_e32 v34, 16, v42
	v_and_b32_e32 v35, 0xffff0000, v43
	v_pk_add_f32 v[32:33], v[36:37], v[32:33]
	v_mov_b32_e32 v57, v59
	v_pk_add_f32 v[34:35], v[56:57], v[34:35]
	v_and_b32_sdwa v36, v33, v232 dst_sel:DWORD dst_unused:UNUSED_PAD src0_sel:WORD_1 src1_sel:DWORD
	v_and_b32_sdwa v37, v32, v232 dst_sel:DWORD dst_unused:UNUSED_PAD src0_sel:WORD_1 src1_sel:DWORD
	v_add3_u32 v33, v33, v36, s81
	v_and_b32_sdwa v36, v35, v232 dst_sel:DWORD dst_unused:UNUSED_PAD src0_sel:WORD_1 src1_sel:DWORD
	v_add3_u32 v32, v32, v37, s81
	v_and_b32_sdwa v37, v34, v232 dst_sel:DWORD dst_unused:UNUSED_PAD src0_sel:WORD_1 src1_sel:DWORD
	v_add3_u32 v35, v35, v36, s81
	v_and_b32_e32 v32, 0xffff0000, v32
	v_add3_u32 v34, v34, v37, s81
	v_and_b32_e32 v35, 0xffff0000, v35
	v_or_b32_sdwa v35, v35, v33 dst_sel:DWORD dst_unused:UNUSED_PAD src0_sel:DWORD src1_sel:WORD_1
	v_or_b32_sdwa v34, v34, v32 dst_sel:DWORD dst_unused:UNUSED_PAD src0_sel:WORD_1 src1_sel:DWORD
	s_waitcnt vmcnt(5)
	v_lshlrev_b32_e32 v33, 16, v69
	v_lshlrev_b32_e32 v32, 16, v68
	v_mov_b32_e32 v38, v46
	v_mov_b32_e32 v39, v40
	v_pk_add_f32 v[38:39], v[38:39], v[32:33]
	global_load_dwordx2 v[32:33], v[160:161], off offset:128
	v_and_b32_e32 v37, 0xffff0000, v69
	v_and_b32_e32 v36, 0xffff0000, v68
	v_mov_b32_e32 v40, v47
	v_pk_add_f32 v[36:37], v[40:41], v[36:37]
	v_and_b32_sdwa v40, v39, v232 dst_sel:DWORD dst_unused:UNUSED_PAD src0_sel:WORD_1 src1_sel:DWORD
	v_and_b32_sdwa v41, v38, v232 dst_sel:DWORD dst_unused:UNUSED_PAD src0_sel:WORD_1 src1_sel:DWORD
	v_add3_u32 v38, v38, v41, s81
	v_add3_u32 v39, v39, v40, s81
	v_and_b32_sdwa v40, v37, v232 dst_sel:DWORD dst_unused:UNUSED_PAD src0_sel:WORD_1 src1_sel:DWORD
	v_and_b32_sdwa v41, v36, v232 dst_sel:DWORD dst_unused:UNUSED_PAD src0_sel:WORD_1 src1_sel:DWORD
	v_add3_u32 v37, v37, v40, s81
	v_add3_u32 v36, v36, v41, s81
	v_and_b32_e32 v37, 0xffff0000, v37
	v_and_b32_e32 v36, 0xffff0000, v36
	v_or_b32_sdwa v37, v37, v39 dst_sel:DWORD dst_unused:UNUSED_PAD src0_sel:DWORD src1_sel:WORD_1
	v_or_b32_sdwa v36, v36, v38 dst_sel:DWORD dst_unused:UNUSED_PAD src0_sel:DWORD src1_sel:WORD_1
	global_store_dwordx2 v[160:161], v[34:35], off offset:32
	global_store_dwordx2 v[160:161], v[36:37], off offset:96
	v_and_b32_e32 v34, 0xffff0000, v72
	v_lshlrev_b32_e32 v35, 16, v73
	v_pk_mov_b32 v[38:39], v[60:61], v[62:63] op_sel:[1,0]
	v_lshlrev_b32_e32 v36, 16, v72
	v_and_b32_e32 v37, 0xffff0000, v73
	v_pk_add_f32 v[38:39], v[38:39], v[34:35]
	global_load_dwordx2 v[34:35], v[160:161], off offset:192
	v_mov_b32_e32 v61, v63
	v_pk_add_f32 v[36:37], v[60:61], v[36:37]
	v_and_b32_sdwa v40, v39, v232 dst_sel:DWORD dst_unused:UNUSED_PAD src0_sel:WORD_1 src1_sel:DWORD
	v_and_b32_sdwa v41, v38, v232 dst_sel:DWORD dst_unused:UNUSED_PAD src0_sel:WORD_1 src1_sel:DWORD
	v_add3_u32 v39, v39, v40, s81
	v_and_b32_sdwa v40, v37, v232 dst_sel:DWORD dst_unused:UNUSED_PAD src0_sel:WORD_1 src1_sel:DWORD
	v_add3_u32 v38, v38, v41, s81
	v_and_b32_sdwa v41, v36, v232 dst_sel:DWORD dst_unused:UNUSED_PAD src0_sel:WORD_1 src1_sel:DWORD
	v_add3_u32 v37, v37, v40, s81
	v_and_b32_e32 v38, 0xffff0000, v38
	v_add3_u32 v36, v36, v41, s81
	v_and_b32_e32 v37, 0xffff0000, v37
	v_or_b32_sdwa v37, v37, v39 dst_sel:DWORD dst_unused:UNUSED_PAD src0_sel:DWORD src1_sel:WORD_1
	v_or_b32_sdwa v36, v36, v38 dst_sel:DWORD dst_unused:UNUSED_PAD src0_sel:WORD_1 src1_sel:DWORD
	s_waitcnt vmcnt(8)
	v_lshlrev_b32_e32 v39, 16, v77
	v_lshlrev_b32_e32 v38, 16, v76
	v_mov_b32_e32 v42, v48
	v_mov_b32_e32 v43, v44
	v_and_b32_e32 v41, 0xffff0000, v77
	v_and_b32_e32 v40, 0xffff0000, v76
	v_pk_add_f32 v[38:39], v[42:43], v[38:39]
	v_mov_b32_e32 v44, v49
	global_load_dwordx2 v[42:43], v[160:161], off offset:144
	v_pk_add_f32 v[40:41], v[44:45], v[40:41]
	v_and_b32_sdwa v44, v39, v232 dst_sel:DWORD dst_unused:UNUSED_PAD src0_sel:WORD_1 src1_sel:DWORD
	v_and_b32_sdwa v45, v38, v232 dst_sel:DWORD dst_unused:UNUSED_PAD src0_sel:WORD_1 src1_sel:DWORD
	v_add3_u32 v38, v38, v45, s81
	v_add3_u32 v39, v39, v44, s81
	v_and_b32_sdwa v44, v41, v232 dst_sel:DWORD dst_unused:UNUSED_PAD src0_sel:WORD_1 src1_sel:DWORD
	v_and_b32_sdwa v45, v40, v232 dst_sel:DWORD dst_unused:UNUSED_PAD src0_sel:WORD_1 src1_sel:DWORD
	v_add3_u32 v41, v41, v44, s81
	v_add3_u32 v40, v40, v45, s81
	v_and_b32_e32 v41, 0xffff0000, v41
	v_and_b32_e32 v40, 0xffff0000, v40
	v_or_b32_sdwa v39, v41, v39 dst_sel:DWORD dst_unused:UNUSED_PAD src0_sel:DWORD src1_sel:WORD_1
	v_or_b32_sdwa v38, v40, v38 dst_sel:DWORD dst_unused:UNUSED_PAD src0_sel:DWORD src1_sel:WORD_1
	global_store_dwordx2 v[160:161], v[36:37], off offset:48
	global_store_dwordx2 v[160:161], v[38:39], off offset:112
	global_load_dwordx2 v[36:37], v[160:161], off offset:208
	v_pk_mul_f32 v[18:19], v[18:19], v[64:65] op_sel_hi:[1,0]
	v_pk_mul_f32 v[38:39], v[16:17], v[64:65] op_sel_hi:[1,0]
	v_pk_mul_f32 v[16:17], v[12:13], v[64:65] op_sel_hi:[1,0]
	v_pk_mul_f32 v[12:13], v[14:15], v[64:65] op_sel_hi:[1,0]
	global_load_dwordx2 v[14:15], v[160:161], off offset:160
	global_load_dwordx2 v[40:41], v[160:161], off offset:176
	v_pk_mov_b32 v[46:47], v[38:39], v[18:19] op_sel:[1,0]
	v_mov_b32_e32 v39, v19
	v_pk_mul_f32 v[0:1], v[0:1], v[64:65] op_sel_hi:[1,0]
	v_pk_mul_f32 v[2:3], v[2:3], v[64:65] op_sel_hi:[1,0]
	v_pk_mul_f32 v[22:23], v[22:23], v[64:65] op_sel_hi:[1,0]
	v_pk_mul_f32 v[20:21], v[20:21], v[64:65] op_sel_hi:[1,0]
	v_pk_mul_f32 v[4:5], v[4:5], v[64:65] op_sel_hi:[1,0]
	v_pk_mul_f32 v[6:7], v[6:7], v[64:65] op_sel_hi:[1,0]
	v_pk_mul_f32 v[26:27], v[26:27], v[64:65] op_sel_hi:[1,0]
	v_pk_mul_f32 v[24:25], v[24:25], v[64:65] op_sel_hi:[1,0]
	v_pk_mul_f32 v[8:9], v[8:9], v[64:65] op_sel_hi:[1,0]
	v_pk_mul_f32 v[10:11], v[10:11], v[64:65] op_sel_hi:[1,0]
	s_waitcnt vmcnt(9)
	v_and_b32_e32 v44, 0xffff0000, v32
	v_lshlrev_b32_e32 v45, 16, v33
	v_lshlrev_b32_e32 v32, 16, v32
	v_and_b32_e32 v33, 0xffff0000, v33
	v_pk_add_f32 v[44:45], v[46:47], v[44:45]
	v_pk_add_f32 v[18:19], v[38:39], v[32:33]
	v_and_b32_sdwa v33, v44, v232 dst_sel:DWORD dst_unused:UNUSED_PAD src0_sel:WORD_1 src1_sel:DWORD
	v_and_b32_sdwa v38, v19, v232 dst_sel:DWORD dst_unused:UNUSED_PAD src0_sel:WORD_1 src1_sel:DWORD
	v_and_b32_sdwa v32, v45, v232 dst_sel:DWORD dst_unused:UNUSED_PAD src0_sel:WORD_1 src1_sel:DWORD
	v_add3_u32 v33, v44, v33, s81
	v_and_b32_sdwa v39, v18, v232 dst_sel:DWORD dst_unused:UNUSED_PAD src0_sel:WORD_1 src1_sel:DWORD
	v_add3_u32 v19, v19, v38, s81
	v_add3_u32 v32, v45, v32, s81
	v_and_b32_e32 v33, 0xffff0000, v33
	v_add3_u32 v18, v18, v39, s81
	v_and_b32_e32 v19, 0xffff0000, v19
	v_or_b32_sdwa v19, v19, v32 dst_sel:DWORD dst_unused:UNUSED_PAD src0_sel:DWORD src1_sel:WORD_1
	v_or_b32_sdwa v18, v18, v33 dst_sel:DWORD dst_unused:UNUSED_PAD src0_sel:WORD_1 src1_sel:DWORD
	global_load_dwordx2 v[32:33], v[160:161], off offset:224
	global_load_dwordx2 v[38:39], v[160:161], off offset:240
	v_mov_b32_e32 v47, v2
	v_mov_b32_e32 v2, v1
	v_mov_b32_e32 v46, v0
	v_pk_mul_f32 v[30:31], v[30:31], v[64:65] op_sel_hi:[1,0]
	v_pk_mul_f32 v[28:29], v[28:29], v[64:65] op_sel_hi:[1,0]
	s_waitcnt vmcnt(8)
	v_lshlrev_b32_e32 v45, 16, v35
	v_lshlrev_b32_e32 v44, 16, v34
	v_and_b32_e32 v35, 0xffff0000, v35
	v_and_b32_e32 v34, 0xffff0000, v34
	v_pk_add_f32 v[0:1], v[2:3], v[34:35]
	v_pk_add_f32 v[44:45], v[46:47], v[44:45]
	v_and_b32_sdwa v34, v1, v232 dst_sel:DWORD dst_unused:UNUSED_PAD src0_sel:WORD_1 src1_sel:DWORD
	v_and_b32_sdwa v35, v0, v232 dst_sel:DWORD dst_unused:UNUSED_PAD src0_sel:WORD_1 src1_sel:DWORD
	v_and_b32_sdwa v2, v45, v232 dst_sel:DWORD dst_unused:UNUSED_PAD src0_sel:WORD_1 src1_sel:DWORD
	v_and_b32_sdwa v3, v44, v232 dst_sel:DWORD dst_unused:UNUSED_PAD src0_sel:WORD_1 src1_sel:DWORD
	v_add3_u32 v1, v1, v34, s81
	v_add3_u32 v0, v0, v35, s81
	v_add3_u32 v3, v44, v3, s81
	v_add3_u32 v2, v45, v2, s81
	v_and_b32_e32 v1, 0xffff0000, v1
	v_and_b32_e32 v0, 0xffff0000, v0
	v_or_b32_sdwa v1, v1, v2 dst_sel:DWORD dst_unused:UNUSED_PAD src0_sel:DWORD src1_sel:WORD_1
	v_or_b32_sdwa v0, v0, v3 dst_sel:DWORD dst_unused:UNUSED_PAD src0_sel:DWORD src1_sel:WORD_1
	global_store_dwordx2 v[160:161], v[18:19], off offset:128
	global_store_dwordx2 v[160:161], v[0:1], off offset:192
	v_pk_mov_b32 v[18:19], v[20:21], v[22:23] op_sel:[1,0]
	v_mov_b32_e32 v21, v23
	v_mov_b32_e32 v23, v163
	v_mov_b32_e32 v22, v163
	s_waitcnt vmcnt(9)
	v_and_b32_e32 v0, 0xffff0000, v42
	v_lshlrev_b32_e32 v1, 16, v43
	v_lshlrev_b32_e32 v2, 16, v42
	v_and_b32_e32 v3, 0xffff0000, v43
	v_pk_add_f32 v[0:1], v[18:19], v[0:1]
	v_pk_add_f32 v[2:3], v[20:21], v[2:3]
	v_and_b32_sdwa v18, v1, v232 dst_sel:DWORD dst_unused:UNUSED_PAD src0_sel:WORD_1 src1_sel:DWORD
	v_and_b32_sdwa v19, v0, v232 dst_sel:DWORD dst_unused:UNUSED_PAD src0_sel:WORD_1 src1_sel:DWORD
	v_add3_u32 v1, v1, v18, s81
	v_and_b32_sdwa v18, v3, v232 dst_sel:DWORD dst_unused:UNUSED_PAD src0_sel:WORD_1 src1_sel:DWORD
	v_add3_u32 v0, v0, v19, s81
	v_and_b32_sdwa v19, v2, v232 dst_sel:DWORD dst_unused:UNUSED_PAD src0_sel:WORD_1 src1_sel:DWORD
	v_add3_u32 v3, v3, v18, s81
	v_and_b32_e32 v0, 0xffff0000, v0
	v_add3_u32 v2, v2, v19, s81
	v_and_b32_e32 v3, 0xffff0000, v3
	v_or_b32_sdwa v1, v3, v1 dst_sel:DWORD dst_unused:UNUSED_PAD src0_sel:DWORD src1_sel:WORD_1
	v_or_b32_sdwa v0, v2, v0 dst_sel:DWORD dst_unused:UNUSED_PAD src0_sel:WORD_1 src1_sel:DWORD
	s_waitcnt vmcnt(6)
	v_lshlrev_b32_e32 v3, 16, v37
	v_lshlrev_b32_e32 v2, 16, v36
	v_mov_b32_e32 v20, v4
	v_mov_b32_e32 v21, v6
	v_and_b32_e32 v19, 0xffff0000, v37
	v_and_b32_e32 v18, 0xffff0000, v36
	v_pk_add_f32 v[2:3], v[20:21], v[2:3]
	v_mov_b32_e32 v6, v5
	v_pk_add_f32 v[4:5], v[6:7], v[18:19]
	v_and_b32_sdwa v6, v3, v232 dst_sel:DWORD dst_unused:UNUSED_PAD src0_sel:WORD_1 src1_sel:DWORD
	v_and_b32_sdwa v7, v2, v232 dst_sel:DWORD dst_unused:UNUSED_PAD src0_sel:WORD_1 src1_sel:DWORD
	v_add3_u32 v2, v2, v7, s81
	v_add3_u32 v3, v3, v6, s81
	v_and_b32_sdwa v6, v5, v232 dst_sel:DWORD dst_unused:UNUSED_PAD src0_sel:WORD_1 src1_sel:DWORD
	v_and_b32_sdwa v7, v4, v232 dst_sel:DWORD dst_unused:UNUSED_PAD src0_sel:WORD_1 src1_sel:DWORD
	v_add3_u32 v5, v5, v6, s81
	v_add3_u32 v4, v4, v7, s81
	v_and_b32_e32 v5, 0xffff0000, v5
	v_and_b32_e32 v4, 0xffff0000, v4
	v_or_b32_sdwa v3, v5, v3 dst_sel:DWORD dst_unused:UNUSED_PAD src0_sel:DWORD src1_sel:WORD_1
	v_or_b32_sdwa v2, v4, v2 dst_sel:DWORD dst_unused:UNUSED_PAD src0_sel:DWORD src1_sel:WORD_1
	global_store_dwordx2 v[160:161], v[0:1], off offset:144
	global_store_dwordx2 v[160:161], v[2:3], off offset:208
	s_waitcnt vmcnt(7)
	v_and_b32_e32 v0, 0xffff0000, v14
	v_lshlrev_b32_e32 v1, 16, v15
	v_pk_mov_b32 v[4:5], v[24:25], v[26:27] op_sel:[1,0]
	v_lshlrev_b32_e32 v2, 16, v14
	v_and_b32_e32 v3, 0xffff0000, v15
	v_pk_add_f32 v[0:1], v[4:5], v[0:1]
	v_mov_b32_e32 v25, v27
	v_pk_add_f32 v[2:3], v[24:25], v[2:3]
	v_and_b32_sdwa v4, v1, v232 dst_sel:DWORD dst_unused:UNUSED_PAD src0_sel:WORD_1 src1_sel:DWORD
	v_and_b32_sdwa v5, v0, v232 dst_sel:DWORD dst_unused:UNUSED_PAD src0_sel:WORD_1 src1_sel:DWORD
	v_add3_u32 v1, v1, v4, s81
	v_and_b32_sdwa v4, v3, v232 dst_sel:DWORD dst_unused:UNUSED_PAD src0_sel:WORD_1 src1_sel:DWORD
	v_add3_u32 v0, v0, v5, s81
	v_and_b32_sdwa v5, v2, v232 dst_sel:DWORD dst_unused:UNUSED_PAD src0_sel:WORD_1 src1_sel:DWORD
	v_add3_u32 v3, v3, v4, s81
	v_and_b32_e32 v0, 0xffff0000, v0
	v_add3_u32 v2, v2, v5, s81
	v_and_b32_e32 v3, 0xffff0000, v3
	v_or_b32_sdwa v1, v3, v1 dst_sel:DWORD dst_unused:UNUSED_PAD src0_sel:DWORD src1_sel:WORD_1
	v_or_b32_sdwa v0, v2, v0 dst_sel:DWORD dst_unused:UNUSED_PAD src0_sel:WORD_1 src1_sel:DWORD
	s_waitcnt vmcnt(5)
	v_lshlrev_b32_e32 v3, 16, v33
	v_lshlrev_b32_e32 v2, 16, v32
	v_mov_b32_e32 v6, v8
	v_mov_b32_e32 v7, v10
	v_and_b32_e32 v5, 0xffff0000, v33
	v_and_b32_e32 v4, 0xffff0000, v32
	v_pk_add_f32 v[2:3], v[6:7], v[2:3]
	v_mov_b32_e32 v10, v9
	v_pk_add_f32 v[4:5], v[10:11], v[4:5]
	v_and_b32_sdwa v6, v3, v232 dst_sel:DWORD dst_unused:UNUSED_PAD src0_sel:WORD_1 src1_sel:DWORD
	v_and_b32_sdwa v7, v2, v232 dst_sel:DWORD dst_unused:UNUSED_PAD src0_sel:WORD_1 src1_sel:DWORD
	v_add3_u32 v2, v2, v7, s81
	v_add3_u32 v3, v3, v6, s81
	v_and_b32_sdwa v6, v5, v232 dst_sel:DWORD dst_unused:UNUSED_PAD src0_sel:WORD_1 src1_sel:DWORD
	v_and_b32_sdwa v7, v4, v232 dst_sel:DWORD dst_unused:UNUSED_PAD src0_sel:WORD_1 src1_sel:DWORD
	v_add3_u32 v5, v5, v6, s81
	v_add3_u32 v4, v4, v7, s81
	v_and_b32_e32 v5, 0xffff0000, v5
	v_and_b32_e32 v4, 0xffff0000, v4
	v_or_b32_sdwa v3, v5, v3 dst_sel:DWORD dst_unused:UNUSED_PAD src0_sel:DWORD src1_sel:WORD_1
	v_or_b32_sdwa v2, v4, v2 dst_sel:DWORD dst_unused:UNUSED_PAD src0_sel:DWORD src1_sel:WORD_1
	global_store_dwordx2 v[160:161], v[0:1], off offset:160
	global_store_dwordx2 v[160:161], v[2:3], off offset:224
	v_and_b32_e32 v0, 0xffff0000, v40
	v_lshlrev_b32_e32 v1, 16, v41
	v_pk_mov_b32 v[4:5], v[28:29], v[30:31] op_sel:[1,0]
	v_lshlrev_b32_e32 v2, 16, v40
	v_and_b32_e32 v3, 0xffff0000, v41
	v_pk_add_f32 v[0:1], v[4:5], v[0:1]
	v_mov_b32_e32 v29, v31
	v_pk_add_f32 v[2:3], v[28:29], v[2:3]
	v_and_b32_sdwa v4, v1, v232 dst_sel:DWORD dst_unused:UNUSED_PAD src0_sel:WORD_1 src1_sel:DWORD
	v_and_b32_sdwa v5, v0, v232 dst_sel:DWORD dst_unused:UNUSED_PAD src0_sel:WORD_1 src1_sel:DWORD
	v_add3_u32 v1, v1, v4, s81
	v_and_b32_sdwa v4, v3, v232 dst_sel:DWORD dst_unused:UNUSED_PAD src0_sel:WORD_1 src1_sel:DWORD
	v_add3_u32 v0, v0, v5, s81
	v_and_b32_sdwa v5, v2, v232 dst_sel:DWORD dst_unused:UNUSED_PAD src0_sel:WORD_1 src1_sel:DWORD
	v_add3_u32 v3, v3, v4, s81
	v_and_b32_e32 v0, 0xffff0000, v0
	v_add3_u32 v2, v2, v5, s81
	v_and_b32_e32 v3, 0xffff0000, v3
	v_or_b32_sdwa v1, v3, v1 dst_sel:DWORD dst_unused:UNUSED_PAD src0_sel:DWORD src1_sel:WORD_1
	v_or_b32_sdwa v0, v2, v0 dst_sel:DWORD dst_unused:UNUSED_PAD src0_sel:WORD_1 src1_sel:DWORD
	s_waitcnt vmcnt(6)
	v_lshlrev_b32_e32 v3, 16, v39
	v_lshlrev_b32_e32 v2, 16, v38
	v_mov_b32_e32 v6, v16
	v_mov_b32_e32 v7, v12
	v_and_b32_e32 v5, 0xffff0000, v39
	v_and_b32_e32 v4, 0xffff0000, v38
	v_pk_add_f32 v[2:3], v[6:7], v[2:3]
	v_mov_b32_e32 v12, v17
	v_pk_add_f32 v[4:5], v[12:13], v[4:5]
	v_and_b32_sdwa v6, v3, v232 dst_sel:DWORD dst_unused:UNUSED_PAD src0_sel:WORD_1 src1_sel:DWORD
	v_and_b32_sdwa v7, v2, v232 dst_sel:DWORD dst_unused:UNUSED_PAD src0_sel:WORD_1 src1_sel:DWORD
	v_add3_u32 v2, v2, v7, s81
	v_add3_u32 v3, v3, v6, s81
	v_and_b32_sdwa v6, v5, v232 dst_sel:DWORD dst_unused:UNUSED_PAD src0_sel:WORD_1 src1_sel:DWORD
	v_and_b32_sdwa v7, v4, v232 dst_sel:DWORD dst_unused:UNUSED_PAD src0_sel:WORD_1 src1_sel:DWORD
	v_add3_u32 v5, v5, v6, s81
	v_add3_u32 v4, v4, v7, s81
	v_and_b32_e32 v5, 0xffff0000, v5
	v_and_b32_e32 v4, 0xffff0000, v4
	v_or_b32_sdwa v3, v5, v3 dst_sel:DWORD dst_unused:UNUSED_PAD src0_sel:DWORD src1_sel:WORD_1
	v_or_b32_sdwa v2, v4, v2 dst_sel:DWORD dst_unused:UNUSED_PAD src0_sel:DWORD src1_sel:WORD_1
	global_store_dwordx2 v[160:161], v[0:1], off offset:176
	global_store_dwordx2 v[160:161], v[2:3], off offset:240
	v_mov_b32_e32 v31, v163
	v_mov_b32_e32 v30, v163
	v_mov_b32_e32 v29, v163
	v_mov_b32_e32 v28, v163
	v_mov_b32_e32 v27, v163
	v_mov_b32_e32 v26, v163
	v_mov_b32_e32 v25, v163
	v_mov_b32_e32 v24, v163
	v_mov_b32_e32 v21, v163
	v_mov_b32_e32 v20, v163
	v_mov_b32_e32 v19, v163
	v_mov_b32_e32 v18, v163
	v_mov_b32_e32 v17, v163
	v_mov_b32_e32 v16, v163
	v_mov_b32_e32 v15, v163
	v_mov_b32_e32 v14, v163
	v_mov_b32_e32 v13, v163
	v_mov_b32_e32 v12, v163
	v_mov_b32_e32 v11, v163
	v_mov_b32_e32 v10, v163
	v_mov_b32_e32 v9, v163
	v_mov_b32_e32 v8, v163
	v_mov_b32_e32 v7, v163
	v_mov_b32_e32 v6, v163
	v_mov_b32_e32 v5, v163
	v_mov_b32_e32 v4, v163
	v_mov_b32_e32 v3, v163
	v_mov_b32_e32 v2, v163
	v_mov_b32_e32 v1, v163
	v_mov_b32_e32 v0, v163
	v_mov_b32_e32 v63, v163
	v_mov_b32_e32 v62, v163
	v_mov_b32_e32 v61, v163
	v_mov_b32_e32 v60, v163
	v_mov_b32_e32 v59, v163
	v_mov_b32_e32 v58, v163
	v_mov_b32_e32 v57, v163
	v_mov_b32_e32 v56, v163
	v_mov_b32_e32 v55, v163
	v_mov_b32_e32 v54, v163
	v_mov_b32_e32 v53, v163
	v_mov_b32_e32 v52, v163
	v_mov_b32_e32 v51, v163
	v_mov_b32_e32 v50, v163
	v_mov_b32_e32 v49, v163
	v_mov_b32_e32 v48, v163
	v_mov_b32_e32 v47, v163
	v_mov_b32_e32 v46, v163
	v_mov_b32_e32 v45, v163
	v_mov_b32_e32 v44, v163
	v_mov_b32_e32 v43, v163
	v_mov_b32_e32 v42, v163
	v_mov_b32_e32 v41, v163
	v_mov_b32_e32 v40, v163
	v_mov_b32_e32 v39, v163
	v_mov_b32_e32 v38, v163
	v_mov_b32_e32 v37, v163
	v_mov_b32_e32 v36, v163
	v_mov_b32_e32 v35, v163
	v_mov_b32_e32 v34, v163
	v_mov_b32_e32 v33, v163
	v_mov_b32_e32 v32, v163
	s_cbranch_scc1 .LBB0_778
	s_cmp_eq_u32 s53, 0
	s_cbranch_scc1 .Lwin_nodelay
	s_sleep 5
.Lwin_nodelay:
	s_lshl_b64 s[0:1], s[0:1], 1
	v_lshl_add_u64 v[210:211], v[202:203], 0, s[0:1]
	s_lshl_b32 s62, s21, 7
	v_lshl_add_u64 v[0:1], v[210:211], 0, s[62:63]
	global_load_dwordx4 v[128:131], v[0:1], off
	global_load_dwordx4 v[132:135], v[0:1], off offset:1024
	global_load_dwordx4 v[136:139], v[0:1], off offset:2048
	global_load_dwordx4 v[140:143], v[0:1], off offset:3072
	v_mov_b32_e32 v32, 0
	v_lshl_add_u64 v[212:213], v[204:205], 0, s[0:1]
	s_add_i32 s3, s3, 1
	s_lshl_b32 s12, s21, 6
	s_add_i32 s16, s91, 0xfffffe20
	v_add_u32_e32 v164, -2, v209
	v_add_u32_e32 v214, -3, v209
	v_add_u32_e32 v215, -8, v209
	v_add_u32_e32 v216, -9, v209
	v_add_u32_e32 v217, -10, v209
	v_add_u32_e32 v218, -11, v209
	v_add_u32_e32 v219, -16, v209
	v_subrev_u32_e32 v235, 17, v209
	v_subrev_u32_e32 v236, 18, v209
	v_subrev_u32_e32 v237, 19, v209
	v_subrev_u32_e32 v238, 24, v209
	v_subrev_u32_e32 v239, 25, v209
	v_subrev_u32_e32 v240, 26, v209
	v_subrev_u32_e32 v241, 27, v209
	v_mov_b32_e32 v33, v32
	v_mov_b32_e32 v34, v32
	v_mov_b32_e32 v35, v32
	v_mov_b32_e32 v36, v32
	v_mov_b32_e32 v37, v32
	v_mov_b32_e32 v38, v32
	v_mov_b32_e32 v39, v32
	v_mov_b32_e32 v40, v32
	v_mov_b32_e32 v41, v32
	v_mov_b32_e32 v42, v32
	v_mov_b32_e32 v43, v32
	v_mov_b32_e32 v44, v32
	v_mov_b32_e32 v45, v32
	v_mov_b32_e32 v46, v32
	v_mov_b32_e32 v47, v32
	v_mov_b32_e32 v48, v32
	v_mov_b32_e32 v49, v32
	v_mov_b32_e32 v50, v32
	v_mov_b32_e32 v51, v32
	v_mov_b32_e32 v52, v32
	v_mov_b32_e32 v53, v32
	v_mov_b32_e32 v54, v32
	v_mov_b32_e32 v55, v32
	v_mov_b32_e32 v56, v32
	v_mov_b32_e32 v57, v32
	v_mov_b32_e32 v58, v32
	v_mov_b32_e32 v59, v32
	v_mov_b32_e32 v60, v32
	v_mov_b32_e32 v61, v32
	v_mov_b32_e32 v62, v32
	v_mov_b32_e32 v63, v32
	v_mov_b32_e32 v0, v32
	v_mov_b32_e32 v1, v32
	v_mov_b32_e32 v2, v32
	v_mov_b32_e32 v3, v32
	v_mov_b32_e32 v4, v32
	v_mov_b32_e32 v5, v32
	v_mov_b32_e32 v6, v32
	v_mov_b32_e32 v7, v32
	v_mov_b32_e32 v8, v32
	v_mov_b32_e32 v9, v32
	v_mov_b32_e32 v10, v32
	v_mov_b32_e32 v11, v32
	v_mov_b32_e32 v12, v32
	v_mov_b32_e32 v13, v32
	v_mov_b32_e32 v14, v32
	v_mov_b32_e32 v15, v32
	v_mov_b32_e32 v16, v32
	v_mov_b32_e32 v17, v32
	v_mov_b32_e32 v18, v32
	v_mov_b32_e32 v19, v32
	v_mov_b32_e32 v20, v32
	v_mov_b32_e32 v21, v32
	v_mov_b32_e32 v22, v32
	v_mov_b32_e32 v23, v32
	v_mov_b32_e32 v24, v32
	v_mov_b32_e32 v25, v32
	v_mov_b32_e32 v26, v32
	v_mov_b32_e32 v27, v32
	v_mov_b32_e32 v28, v32
	v_mov_b32_e32 v29, v32
	v_mov_b32_e32 v30, v32
	v_mov_b32_e32 v31, v32
	v_mov_b32_e32 v162, v32
	v_mov_b32_e32 v163, v32
